# D3 scan rewritten: all loads up front, counted vmcnt, no per-step round trips
# speedup vs baseline: 1.0109x; 1.0109x over previous
.LBB0_471:
	s_or_b64 exec, exec, s[4:5]
	v_readlane_b32 s0, v252, 0
	s_lshl_b32 s67, s0, 9
	s_waitcnt lgkmcnt(0)
	v_mov_b32_e32 v0, v182
	s_barrier
	s_lshl_b32 s66, s96, 9
	s_mov_b32 s6, s67
.Ld3_loop:
	s_cmp_lt_u32 s6, 0x20000
	s_cbranch_scc0 .Ld3_part2
	s_lshr_b32 s7, s6, 14
	s_lshl_b32 s8, s7, 7
	s_lshl_b32 s9, s7, 22
	s_add_u32 s10, s58, 0x340000
	s_addc_u32 s11, s59, 0
	s_add_u32 s10, s10, s8
	s_addc_u32 s11, s11, 0
	s_add_u32 s12, s10, 0x1000
	s_addc_u32 s13, s11, 0
	v_mov_b32_e32 v29, 0
	global_load_dwordx4 v[90:93], v29, s[10:11] offset:0
	global_load_dwordx4 v[94:97], v29, s[10:11] offset:16
	global_load_dwordx4 v[98:101], v29, s[10:11] offset:32
	global_load_dwordx4 v[102:105], v29, s[10:11] offset:48
	global_load_dwordx4 v[106:109], v29, s[10:11] offset:64
	global_load_dwordx4 v[110:113], v29, s[10:11] offset:80
	global_load_dwordx4 v[114:117], v29, s[10:11] offset:96
	global_load_dwordx4 v[118:121], v29, s[10:11] offset:112
	global_load_dwordx4 v[122:125], v29, s[12:13] offset:0
	global_load_dwordx4 v[126:129], v29, s[12:13] offset:16
	global_load_dwordx4 v[130:133], v29, s[12:13] offset:32
	global_load_dwordx4 v[134:137], v29, s[12:13] offset:48
	global_load_dwordx4 v[138:141], v29, s[12:13] offset:64
	global_load_dwordx4 v[142:145], v29, s[12:13] offset:80
	global_load_dwordx4 v[146:149], v29, s[12:13] offset:96
	global_load_dwordx4 v[150:153], v29, s[12:13] offset:112
	s_and_b32 s14, s6, 0x3fff
	v_add_u32_e32 v30, s14, v182
	v_lshlrev_b32_e32 v30, 3, v30
	s_add_u32 s0, s58, 0x2400000
	s_addc_u32 s1, s59, 0
	s_add_u32 s0, s0, s9
	s_addc_u32 s1, s1, 0
	global_load_dwordx2 v[184:185], v30, s[0:1] nt
	s_add_u32 s0, s0, 0x20000
	s_addc_u32 s1, s1, 0
	global_load_dwordx2 v[186:187], v30, s[0:1] nt
	s_add_u32 s0, s0, 0x20000
	s_addc_u32 s1, s1, 0
	global_load_dwordx2 v[188:189], v30, s[0:1] nt
	s_add_u32 s0, s0, 0x20000
	s_addc_u32 s1, s1, 0
	global_load_dwordx2 v[190:191], v30, s[0:1] nt
	s_add_u32 s0, s0, 0x20000
	s_addc_u32 s1, s1, 0
	global_load_dwordx2 v[192:193], v30, s[0:1] nt
	s_add_u32 s0, s0, 0x20000
	s_addc_u32 s1, s1, 0
	global_load_dwordx2 v[194:195], v30, s[0:1] nt
	s_add_u32 s0, s0, 0x20000
	s_addc_u32 s1, s1, 0
	global_load_dwordx2 v[196:197], v30, s[0:1] nt
	s_add_u32 s0, s0, 0x20000
	s_addc_u32 s1, s1, 0
	global_load_dwordx2 v[198:199], v30, s[0:1] nt
	s_add_u32 s0, s0, 0x20000
	s_addc_u32 s1, s1, 0
	global_load_dwordx2 v[200:201], v30, s[0:1] nt
	s_add_u32 s0, s0, 0x20000
	s_addc_u32 s1, s1, 0
	global_load_dwordx2 v[202:203], v30, s[0:1] nt
	s_add_u32 s0, s0, 0x20000
	s_addc_u32 s1, s1, 0
	global_load_dwordx2 v[204:205], v30, s[0:1] nt
	s_add_u32 s0, s0, 0x20000
	s_addc_u32 s1, s1, 0
	global_load_dwordx2 v[206:207], v30, s[0:1] nt
	s_add_u32 s0, s0, 0x20000
	s_addc_u32 s1, s1, 0
	global_load_dwordx2 v[208:209], v30, s[0:1] nt
	s_add_u32 s0, s0, 0x20000
	s_addc_u32 s1, s1, 0
	global_load_dwordx2 v[210:211], v30, s[0:1] nt
	s_add_u32 s0, s0, 0x20000
	s_addc_u32 s1, s1, 0
	global_load_dwordx2 v[212:213], v30, s[0:1] nt
	s_add_u32 s0, s0, 0x20000
	s_addc_u32 s1, s1, 0
	global_load_dwordx2 v[214:215], v30, s[0:1] nt
	s_add_u32 s0, s0, 0x20000
	s_addc_u32 s1, s1, 0
	global_load_dwordx2 v[216:217], v30, s[0:1] nt
	s_add_u32 s0, s0, 0x20000
	s_addc_u32 s1, s1, 0
	global_load_dwordx2 v[218:219], v30, s[0:1] nt
	s_add_u32 s0, s0, 0x20000
	s_addc_u32 s1, s1, 0
	global_load_dwordx2 v[220:221], v30, s[0:1] nt
	s_add_u32 s0, s0, 0x20000
	s_addc_u32 s1, s1, 0
	global_load_dwordx2 v[222:223], v30, s[0:1] nt
	s_add_u32 s0, s0, 0x20000
	s_addc_u32 s1, s1, 0
	global_load_dwordx2 v[224:225], v30, s[0:1] nt
	s_add_u32 s0, s0, 0x20000
	s_addc_u32 s1, s1, 0
	global_load_dwordx2 v[226:227], v30, s[0:1] nt
	s_add_u32 s0, s0, 0x20000
	s_addc_u32 s1, s1, 0
	global_load_dwordx2 v[228:229], v30, s[0:1] nt
	s_add_u32 s0, s0, 0x20000
	s_addc_u32 s1, s1, 0
	global_load_dwordx2 v[230:231], v30, s[0:1] nt
	s_add_u32 s0, s0, 0x20000
	s_addc_u32 s1, s1, 0
	global_load_dwordx2 v[232:233], v30, s[0:1] nt
	s_add_u32 s0, s0, 0x20000
	s_addc_u32 s1, s1, 0
	global_load_dwordx2 v[234:235], v30, s[0:1] nt
	s_add_u32 s0, s0, 0x20000
	s_addc_u32 s1, s1, 0
	global_load_dwordx2 v[236:237], v30, s[0:1] nt
	s_add_u32 s0, s0, 0x20000
	s_addc_u32 s1, s1, 0
	global_load_dwordx2 v[238:239], v30, s[0:1] nt
	s_add_u32 s0, s0, 0x20000
	s_addc_u32 s1, s1, 0
	global_load_dwordx2 v[240:241], v30, s[0:1] nt
	s_add_u32 s0, s0, 0x20000
	s_addc_u32 s1, s1, 0
	global_load_dwordx2 v[242:243], v30, s[0:1] nt
	s_add_u32 s0, s0, 0x20000
	s_addc_u32 s1, s1, 0
	global_load_dwordx2 v[244:245], v30, s[0:1] nt
	s_add_u32 s0, s0, 0x20000
	s_addc_u32 s1, s1, 0
	global_load_dwordx2 v[246:247], v30, s[0:1] nt
	s_add_u32 s2, s58, 0x12800000
	s_addc_u32 s3, s59, 0
	s_add_u32 s2, s2, s9
	s_addc_u32 s3, s3, 0
	s_waitcnt vmcnt(32)
	v_mov_b32_e32 v31, 0
	v_mov_b32_e32 v49, v31
	v_add_f32_e32 v90, v31, v90
	v_max_f32_e32 v32, v122, v122
	v_max_f32_e32 v31, v90, v32
	v_sub_f32_e32 v90, v90, v31
	v_sub_f32_e32 v122, v122, v31
	v_mul_f32_e32 v90, 0x3fb8aa3b, v90
	v_mul_f32_e32 v122, 0x3fb8aa3b, v122
	v_exp_f32_e32 v90, v90
	v_exp_f32_e32 v122, v122
	v_mov_b32_e32 v50, v31
	v_add_f32_e32 v91, v31, v91
	v_max_f32_e32 v32, v123, v123
	v_max_f32_e32 v31, v91, v32
	v_sub_f32_e32 v91, v91, v31
	v_sub_f32_e32 v123, v123, v31
	v_mul_f32_e32 v91, 0x3fb8aa3b, v91
	v_mul_f32_e32 v123, 0x3fb8aa3b, v123
	v_exp_f32_e32 v91, v91
	v_exp_f32_e32 v123, v123
	v_mov_b32_e32 v51, v31
	v_add_f32_e32 v92, v31, v92
	v_max_f32_e32 v32, v124, v124
	v_max_f32_e32 v31, v92, v32
	v_sub_f32_e32 v92, v92, v31
	v_sub_f32_e32 v124, v124, v31
	v_mul_f32_e32 v92, 0x3fb8aa3b, v92
	v_mul_f32_e32 v124, 0x3fb8aa3b, v124
	v_exp_f32_e32 v92, v92
	v_exp_f32_e32 v124, v124
	v_mov_b32_e32 v52, v31
	v_add_f32_e32 v93, v31, v93
	v_max_f32_e32 v32, v125, v125
	v_max_f32_e32 v31, v93, v32
	v_sub_f32_e32 v93, v93, v31
	v_sub_f32_e32 v125, v125, v31
	v_mul_f32_e32 v93, 0x3fb8aa3b, v93
	v_mul_f32_e32 v125, 0x3fb8aa3b, v125
	v_exp_f32_e32 v93, v93
	v_exp_f32_e32 v125, v125
	v_mov_b32_e32 v53, v31
	v_add_f32_e32 v94, v31, v94
	v_max_f32_e32 v32, v126, v126
	v_max_f32_e32 v31, v94, v32
	v_sub_f32_e32 v94, v94, v31
	v_sub_f32_e32 v126, v126, v31
	v_mul_f32_e32 v94, 0x3fb8aa3b, v94
	v_mul_f32_e32 v126, 0x3fb8aa3b, v126
	v_exp_f32_e32 v94, v94
	v_exp_f32_e32 v126, v126
	v_mov_b32_e32 v54, v31
	v_add_f32_e32 v95, v31, v95
	v_max_f32_e32 v32, v127, v127
	v_max_f32_e32 v31, v95, v32
	v_sub_f32_e32 v95, v95, v31
	v_sub_f32_e32 v127, v127, v31
	v_mul_f32_e32 v95, 0x3fb8aa3b, v95
	v_mul_f32_e32 v127, 0x3fb8aa3b, v127
	v_exp_f32_e32 v95, v95
	v_exp_f32_e32 v127, v127
	v_mov_b32_e32 v55, v31
	v_add_f32_e32 v96, v31, v96
	v_max_f32_e32 v32, v128, v128
	v_max_f32_e32 v31, v96, v32
	v_sub_f32_e32 v96, v96, v31
	v_sub_f32_e32 v128, v128, v31
	v_mul_f32_e32 v96, 0x3fb8aa3b, v96
	v_mul_f32_e32 v128, 0x3fb8aa3b, v128
	v_exp_f32_e32 v96, v96
	v_exp_f32_e32 v128, v128
	v_mov_b32_e32 v56, v31
	v_add_f32_e32 v97, v31, v97
	v_max_f32_e32 v32, v129, v129
	v_max_f32_e32 v31, v97, v32
	v_sub_f32_e32 v97, v97, v31
	v_sub_f32_e32 v129, v129, v31
	v_mul_f32_e32 v97, 0x3fb8aa3b, v97
	v_mul_f32_e32 v129, 0x3fb8aa3b, v129
	v_exp_f32_e32 v97, v97
	v_exp_f32_e32 v129, v129
	v_mov_b32_e32 v57, v31
	v_add_f32_e32 v98, v31, v98
	v_max_f32_e32 v32, v130, v130
	v_max_f32_e32 v31, v98, v32
	v_sub_f32_e32 v98, v98, v31
	v_sub_f32_e32 v130, v130, v31
	v_mul_f32_e32 v98, 0x3fb8aa3b, v98
	v_mul_f32_e32 v130, 0x3fb8aa3b, v130
	v_exp_f32_e32 v98, v98
	v_exp_f32_e32 v130, v130
	v_mov_b32_e32 v58, v31
	v_add_f32_e32 v99, v31, v99
	v_max_f32_e32 v32, v131, v131
	v_max_f32_e32 v31, v99, v32
	v_sub_f32_e32 v99, v99, v31
	v_sub_f32_e32 v131, v131, v31
	v_mul_f32_e32 v99, 0x3fb8aa3b, v99
	v_mul_f32_e32 v131, 0x3fb8aa3b, v131
	v_exp_f32_e32 v99, v99
	v_exp_f32_e32 v131, v131
	v_mov_b32_e32 v59, v31
	v_add_f32_e32 v100, v31, v100
	v_max_f32_e32 v32, v132, v132
	v_max_f32_e32 v31, v100, v32
	v_sub_f32_e32 v100, v100, v31
	v_sub_f32_e32 v132, v132, v31
	v_mul_f32_e32 v100, 0x3fb8aa3b, v100
	v_mul_f32_e32 v132, 0x3fb8aa3b, v132
	v_exp_f32_e32 v100, v100
	v_exp_f32_e32 v132, v132
	v_mov_b32_e32 v60, v31
	v_add_f32_e32 v101, v31, v101
	v_max_f32_e32 v32, v133, v133
	v_max_f32_e32 v31, v101, v32
	v_sub_f32_e32 v101, v101, v31
	v_sub_f32_e32 v133, v133, v31
	v_mul_f32_e32 v101, 0x3fb8aa3b, v101
	v_mul_f32_e32 v133, 0x3fb8aa3b, v133
	v_exp_f32_e32 v101, v101
	v_exp_f32_e32 v133, v133
	v_mov_b32_e32 v61, v31
	v_add_f32_e32 v102, v31, v102
	v_max_f32_e32 v32, v134, v134
	v_max_f32_e32 v31, v102, v32
	v_sub_f32_e32 v102, v102, v31
	v_sub_f32_e32 v134, v134, v31
	v_mul_f32_e32 v102, 0x3fb8aa3b, v102
	v_mul_f32_e32 v134, 0x3fb8aa3b, v134
	v_exp_f32_e32 v102, v102
	v_exp_f32_e32 v134, v134
	v_mov_b32_e32 v62, v31
	v_add_f32_e32 v103, v31, v103
	v_max_f32_e32 v32, v135, v135
	v_max_f32_e32 v31, v103, v32
	v_sub_f32_e32 v103, v103, v31
	v_sub_f32_e32 v135, v135, v31
	v_mul_f32_e32 v103, 0x3fb8aa3b, v103
	v_mul_f32_e32 v135, 0x3fb8aa3b, v135
	v_exp_f32_e32 v103, v103
	v_exp_f32_e32 v135, v135
	v_mov_b32_e32 v63, v31
	v_add_f32_e32 v104, v31, v104
	v_max_f32_e32 v32, v136, v136
	v_max_f32_e32 v31, v104, v32
	v_sub_f32_e32 v104, v104, v31
	v_sub_f32_e32 v136, v136, v31
	v_mul_f32_e32 v104, 0x3fb8aa3b, v104
	v_mul_f32_e32 v136, 0x3fb8aa3b, v136
	v_exp_f32_e32 v104, v104
	v_exp_f32_e32 v136, v136
	v_mov_b32_e32 v64, v31
	v_add_f32_e32 v105, v31, v105
	v_max_f32_e32 v32, v137, v137
	v_max_f32_e32 v31, v105, v32
	v_sub_f32_e32 v105, v105, v31
	v_sub_f32_e32 v137, v137, v31
	v_mul_f32_e32 v105, 0x3fb8aa3b, v105
	v_mul_f32_e32 v137, 0x3fb8aa3b, v137
	v_exp_f32_e32 v105, v105
	v_exp_f32_e32 v137, v137
	v_mov_b32_e32 v65, v31
	v_add_f32_e32 v106, v31, v106
	v_max_f32_e32 v32, v138, v138
	v_max_f32_e32 v31, v106, v32
	v_sub_f32_e32 v106, v106, v31
	v_sub_f32_e32 v138, v138, v31
	v_mul_f32_e32 v106, 0x3fb8aa3b, v106
	v_mul_f32_e32 v138, 0x3fb8aa3b, v138
	v_exp_f32_e32 v106, v106
	v_exp_f32_e32 v138, v138
	v_mov_b32_e32 v66, v31
	v_add_f32_e32 v107, v31, v107
	v_max_f32_e32 v32, v139, v139
	v_max_f32_e32 v31, v107, v32
	v_sub_f32_e32 v107, v107, v31
	v_sub_f32_e32 v139, v139, v31
	v_mul_f32_e32 v107, 0x3fb8aa3b, v107
	v_mul_f32_e32 v139, 0x3fb8aa3b, v139
	v_exp_f32_e32 v107, v107
	v_exp_f32_e32 v139, v139
	v_mov_b32_e32 v67, v31
	v_add_f32_e32 v108, v31, v108
	v_max_f32_e32 v32, v140, v140
	v_max_f32_e32 v31, v108, v32
	v_sub_f32_e32 v108, v108, v31
	v_sub_f32_e32 v140, v140, v31
	v_mul_f32_e32 v108, 0x3fb8aa3b, v108
	v_mul_f32_e32 v140, 0x3fb8aa3b, v140
	v_exp_f32_e32 v108, v108
	v_exp_f32_e32 v140, v140
	v_mov_b32_e32 v68, v31
	v_add_f32_e32 v109, v31, v109
	v_max_f32_e32 v32, v141, v141
	v_max_f32_e32 v31, v109, v32
	v_sub_f32_e32 v109, v109, v31
	v_sub_f32_e32 v141, v141, v31
	v_mul_f32_e32 v109, 0x3fb8aa3b, v109
	v_mul_f32_e32 v141, 0x3fb8aa3b, v141
	v_exp_f32_e32 v109, v109
	v_exp_f32_e32 v141, v141
	v_mov_b32_e32 v69, v31
	v_add_f32_e32 v110, v31, v110
	v_max_f32_e32 v32, v142, v142
	v_max_f32_e32 v31, v110, v32
	v_sub_f32_e32 v110, v110, v31
	v_sub_f32_e32 v142, v142, v31
	v_mul_f32_e32 v110, 0x3fb8aa3b, v110
	v_mul_f32_e32 v142, 0x3fb8aa3b, v142
	v_exp_f32_e32 v110, v110
	v_exp_f32_e32 v142, v142
	v_mov_b32_e32 v70, v31
	v_add_f32_e32 v111, v31, v111
	v_max_f32_e32 v32, v143, v143
	v_max_f32_e32 v31, v111, v32
	v_sub_f32_e32 v111, v111, v31
	v_sub_f32_e32 v143, v143, v31
	v_mul_f32_e32 v111, 0x3fb8aa3b, v111
	v_mul_f32_e32 v143, 0x3fb8aa3b, v143
	v_exp_f32_e32 v111, v111
	v_exp_f32_e32 v143, v143
	v_mov_b32_e32 v71, v31
	v_add_f32_e32 v112, v31, v112
	v_max_f32_e32 v32, v144, v144
	v_max_f32_e32 v31, v112, v32
	v_sub_f32_e32 v112, v112, v31
	v_sub_f32_e32 v144, v144, v31
	v_mul_f32_e32 v112, 0x3fb8aa3b, v112
	v_mul_f32_e32 v144, 0x3fb8aa3b, v144
	v_exp_f32_e32 v112, v112
	v_exp_f32_e32 v144, v144
	v_mov_b32_e32 v72, v31
	v_add_f32_e32 v113, v31, v113
	v_max_f32_e32 v32, v145, v145
	v_max_f32_e32 v31, v113, v32
	v_sub_f32_e32 v113, v113, v31
	v_sub_f32_e32 v145, v145, v31
	v_mul_f32_e32 v113, 0x3fb8aa3b, v113
	v_mul_f32_e32 v145, 0x3fb8aa3b, v145
	v_exp_f32_e32 v113, v113
	v_exp_f32_e32 v145, v145
	v_mov_b32_e32 v73, v31
	v_add_f32_e32 v114, v31, v114
	v_max_f32_e32 v32, v146, v146
	v_max_f32_e32 v31, v114, v32
	v_sub_f32_e32 v114, v114, v31
	v_sub_f32_e32 v146, v146, v31
	v_mul_f32_e32 v114, 0x3fb8aa3b, v114
	v_mul_f32_e32 v146, 0x3fb8aa3b, v146
	v_exp_f32_e32 v114, v114
	v_exp_f32_e32 v146, v146
	v_mov_b32_e32 v74, v31
	v_add_f32_e32 v115, v31, v115
	v_max_f32_e32 v32, v147, v147
	v_max_f32_e32 v31, v115, v32
	v_sub_f32_e32 v115, v115, v31
	v_sub_f32_e32 v147, v147, v31
	v_mul_f32_e32 v115, 0x3fb8aa3b, v115
	v_mul_f32_e32 v147, 0x3fb8aa3b, v147
	v_exp_f32_e32 v115, v115
	v_exp_f32_e32 v147, v147
	v_mov_b32_e32 v75, v31
	v_add_f32_e32 v116, v31, v116
	v_max_f32_e32 v32, v148, v148
	v_max_f32_e32 v31, v116, v32
	v_sub_f32_e32 v116, v116, v31
	v_sub_f32_e32 v148, v148, v31
	v_mul_f32_e32 v116, 0x3fb8aa3b, v116
	v_mul_f32_e32 v148, 0x3fb8aa3b, v148
	v_exp_f32_e32 v116, v116
	v_exp_f32_e32 v148, v148
	v_mov_b32_e32 v76, v31
	v_add_f32_e32 v117, v31, v117
	v_max_f32_e32 v32, v149, v149
	v_max_f32_e32 v31, v117, v32
	v_sub_f32_e32 v117, v117, v31
	v_sub_f32_e32 v149, v149, v31
	v_mul_f32_e32 v117, 0x3fb8aa3b, v117
	v_mul_f32_e32 v149, 0x3fb8aa3b, v149
	v_exp_f32_e32 v117, v117
	v_exp_f32_e32 v149, v149
	v_mov_b32_e32 v77, v31
	v_add_f32_e32 v118, v31, v118
	v_max_f32_e32 v32, v150, v150
	v_max_f32_e32 v31, v118, v32
	v_sub_f32_e32 v118, v118, v31
	v_sub_f32_e32 v150, v150, v31
	v_mul_f32_e32 v118, 0x3fb8aa3b, v118
	v_mul_f32_e32 v150, 0x3fb8aa3b, v150
	v_exp_f32_e32 v118, v118
	v_exp_f32_e32 v150, v150
	v_mov_b32_e32 v78, v31
	v_add_f32_e32 v119, v31, v119
	v_max_f32_e32 v32, v151, v151
	v_max_f32_e32 v31, v119, v32
	v_sub_f32_e32 v119, v119, v31
	v_sub_f32_e32 v151, v151, v31
	v_mul_f32_e32 v119, 0x3fb8aa3b, v119
	v_mul_f32_e32 v151, 0x3fb8aa3b, v151
	v_exp_f32_e32 v119, v119
	v_exp_f32_e32 v151, v151
	v_mov_b32_e32 v79, v31
	v_add_f32_e32 v120, v31, v120
	v_max_f32_e32 v32, v152, v152
	v_max_f32_e32 v31, v120, v32
	v_sub_f32_e32 v120, v120, v31
	v_sub_f32_e32 v152, v152, v31
	v_mul_f32_e32 v120, 0x3fb8aa3b, v120
	v_mul_f32_e32 v152, 0x3fb8aa3b, v152
	v_exp_f32_e32 v120, v120
	v_exp_f32_e32 v152, v152
	v_mov_b32_e32 v80, v31
	v_add_f32_e32 v121, v31, v121
	v_max_f32_e32 v32, v153, v153
	v_max_f32_e32 v31, v121, v32
	v_sub_f32_e32 v121, v121, v31
	v_sub_f32_e32 v153, v153, v31
	v_mul_f32_e32 v121, 0x3fb8aa3b, v121
	v_mul_f32_e32 v153, 0x3fb8aa3b, v153
	v_exp_f32_e32 v121, v121
	v_exp_f32_e32 v153, v153
	v_mov_b32_e32 v24, 0
	v_mov_b32_e32 v25, 0
	v_mov_b32_e32 v26, 0
	v_mov_b32_e32 v27, 0
	v_cvt_pk_bf16_f32 v28, v24, v25
	v_cvt_pk_bf16_f32 v29, v26, v27
	global_store_dwordx2 v30, v[28:29], s[2:3]
	s_add_u32 s2, s2, 0x20000
	s_addc_u32 s3, s3, 0
	s_waitcnt vmcnt(32)
	v_lshlrev_b32_e32 v38, 16, v184
	v_and_b32_e32 v39, 0xffff0000, v184
	v_lshlrev_b32_e32 v40, 16, v185
	v_and_b32_e32 v41, 0xffff0000, v185
	v_mul_f32_e32 v24, v24, v90
	v_mul_f32_e32 v25, v25, v90
	v_mul_f32_e32 v26, v26, v90
	v_mul_f32_e32 v27, v27, v90
	v_fmac_f32_e32 v24, v122, v38
	v_fmac_f32_e32 v25, v122, v39
	v_fmac_f32_e32 v26, v122, v40
	v_fmac_f32_e32 v27, v122, v41
	v_cvt_pk_bf16_f32 v36, v24, v25
	v_cvt_pk_bf16_f32 v37, v26, v27
	global_store_dwordx2 v30, v[36:37], s[2:3]
	s_add_u32 s2, s2, 0x20000
	s_addc_u32 s3, s3, 0
	s_waitcnt vmcnt(32)
	v_lshlrev_b32_e32 v38, 16, v186
	v_and_b32_e32 v39, 0xffff0000, v186
	v_lshlrev_b32_e32 v40, 16, v187
	v_and_b32_e32 v41, 0xffff0000, v187
	v_mul_f32_e32 v24, v24, v91
	v_mul_f32_e32 v25, v25, v91
	v_mul_f32_e32 v26, v26, v91
	v_mul_f32_e32 v27, v27, v91
	v_fmac_f32_e32 v24, v123, v38
	v_fmac_f32_e32 v25, v123, v39
	v_fmac_f32_e32 v26, v123, v40
	v_fmac_f32_e32 v27, v123, v41
	v_cvt_pk_bf16_f32 v28, v24, v25
	v_cvt_pk_bf16_f32 v29, v26, v27
	global_store_dwordx2 v30, v[28:29], s[2:3]
	s_add_u32 s2, s2, 0x20000
	s_addc_u32 s3, s3, 0
	s_waitcnt vmcnt(32)
	v_lshlrev_b32_e32 v38, 16, v188
	v_and_b32_e32 v39, 0xffff0000, v188
	v_lshlrev_b32_e32 v40, 16, v189
	v_and_b32_e32 v41, 0xffff0000, v189
	v_mul_f32_e32 v24, v24, v92
	v_mul_f32_e32 v25, v25, v92
	v_mul_f32_e32 v26, v26, v92
	v_mul_f32_e32 v27, v27, v92
	v_fmac_f32_e32 v24, v124, v38
	v_fmac_f32_e32 v25, v124, v39
	v_fmac_f32_e32 v26, v124, v40
	v_fmac_f32_e32 v27, v124, v41
	v_cvt_pk_bf16_f32 v36, v24, v25
	v_cvt_pk_bf16_f32 v37, v26, v27
	global_store_dwordx2 v30, v[36:37], s[2:3]
	s_add_u32 s2, s2, 0x20000
	s_addc_u32 s3, s3, 0
	s_waitcnt vmcnt(32)
	v_lshlrev_b32_e32 v38, 16, v190
	v_and_b32_e32 v39, 0xffff0000, v190
	v_lshlrev_b32_e32 v40, 16, v191
	v_and_b32_e32 v41, 0xffff0000, v191
	v_mul_f32_e32 v24, v24, v93
	v_mul_f32_e32 v25, v25, v93
	v_mul_f32_e32 v26, v26, v93
	v_mul_f32_e32 v27, v27, v93
	v_fmac_f32_e32 v24, v125, v38
	v_fmac_f32_e32 v25, v125, v39
	v_fmac_f32_e32 v26, v125, v40
	v_fmac_f32_e32 v27, v125, v41
	v_cvt_pk_bf16_f32 v28, v24, v25
	v_cvt_pk_bf16_f32 v29, v26, v27
	global_store_dwordx2 v30, v[28:29], s[2:3]
	s_add_u32 s2, s2, 0x20000
	s_addc_u32 s3, s3, 0
	s_waitcnt vmcnt(32)
	v_lshlrev_b32_e32 v38, 16, v192
	v_and_b32_e32 v39, 0xffff0000, v192
	v_lshlrev_b32_e32 v40, 16, v193
	v_and_b32_e32 v41, 0xffff0000, v193
	v_mul_f32_e32 v24, v24, v94
	v_mul_f32_e32 v25, v25, v94
	v_mul_f32_e32 v26, v26, v94
	v_mul_f32_e32 v27, v27, v94
	v_fmac_f32_e32 v24, v126, v38
	v_fmac_f32_e32 v25, v126, v39
	v_fmac_f32_e32 v26, v126, v40
	v_fmac_f32_e32 v27, v126, v41
	v_cvt_pk_bf16_f32 v36, v24, v25
	v_cvt_pk_bf16_f32 v37, v26, v27
	global_store_dwordx2 v30, v[36:37], s[2:3]
	s_add_u32 s2, s2, 0x20000
	s_addc_u32 s3, s3, 0
	s_waitcnt vmcnt(32)
	v_lshlrev_b32_e32 v38, 16, v194
	v_and_b32_e32 v39, 0xffff0000, v194
	v_lshlrev_b32_e32 v40, 16, v195
	v_and_b32_e32 v41, 0xffff0000, v195
	v_mul_f32_e32 v24, v24, v95
	v_mul_f32_e32 v25, v25, v95
	v_mul_f32_e32 v26, v26, v95
	v_mul_f32_e32 v27, v27, v95
	v_fmac_f32_e32 v24, v127, v38
	v_fmac_f32_e32 v25, v127, v39
	v_fmac_f32_e32 v26, v127, v40
	v_fmac_f32_e32 v27, v127, v41
	v_cvt_pk_bf16_f32 v28, v24, v25
	v_cvt_pk_bf16_f32 v29, v26, v27
	global_store_dwordx2 v30, v[28:29], s[2:3]
	s_add_u32 s2, s2, 0x20000
	s_addc_u32 s3, s3, 0
	s_waitcnt vmcnt(32)
	v_lshlrev_b32_e32 v38, 16, v196
	v_and_b32_e32 v39, 0xffff0000, v196
	v_lshlrev_b32_e32 v40, 16, v197
	v_and_b32_e32 v41, 0xffff0000, v197
	v_mul_f32_e32 v24, v24, v96
	v_mul_f32_e32 v25, v25, v96
	v_mul_f32_e32 v26, v26, v96
	v_mul_f32_e32 v27, v27, v96
	v_fmac_f32_e32 v24, v128, v38
	v_fmac_f32_e32 v25, v128, v39
	v_fmac_f32_e32 v26, v128, v40
	v_fmac_f32_e32 v27, v128, v41
	v_cvt_pk_bf16_f32 v36, v24, v25
	v_cvt_pk_bf16_f32 v37, v26, v27
	global_store_dwordx2 v30, v[36:37], s[2:3]
	s_add_u32 s2, s2, 0x20000
	s_addc_u32 s3, s3, 0
	s_waitcnt vmcnt(32)
	v_lshlrev_b32_e32 v38, 16, v198
	v_and_b32_e32 v39, 0xffff0000, v198
	v_lshlrev_b32_e32 v40, 16, v199
	v_and_b32_e32 v41, 0xffff0000, v199
	v_mul_f32_e32 v24, v24, v97
	v_mul_f32_e32 v25, v25, v97
	v_mul_f32_e32 v26, v26, v97
	v_mul_f32_e32 v27, v27, v97
	v_fmac_f32_e32 v24, v129, v38
	v_fmac_f32_e32 v25, v129, v39
	v_fmac_f32_e32 v26, v129, v40
	v_fmac_f32_e32 v27, v129, v41
	v_cvt_pk_bf16_f32 v28, v24, v25
	v_cvt_pk_bf16_f32 v29, v26, v27
	global_store_dwordx2 v30, v[28:29], s[2:3]
	s_add_u32 s2, s2, 0x20000
	s_addc_u32 s3, s3, 0
	s_waitcnt vmcnt(32)
	v_lshlrev_b32_e32 v38, 16, v200
	v_and_b32_e32 v39, 0xffff0000, v200
	v_lshlrev_b32_e32 v40, 16, v201
	v_and_b32_e32 v41, 0xffff0000, v201
	v_mul_f32_e32 v24, v24, v98
	v_mul_f32_e32 v25, v25, v98
	v_mul_f32_e32 v26, v26, v98
	v_mul_f32_e32 v27, v27, v98
	v_fmac_f32_e32 v24, v130, v38
	v_fmac_f32_e32 v25, v130, v39
	v_fmac_f32_e32 v26, v130, v40
	v_fmac_f32_e32 v27, v130, v41
	v_cvt_pk_bf16_f32 v36, v24, v25
	v_cvt_pk_bf16_f32 v37, v26, v27
	global_store_dwordx2 v30, v[36:37], s[2:3]
	s_add_u32 s2, s2, 0x20000
	s_addc_u32 s3, s3, 0
	s_waitcnt vmcnt(32)
	v_lshlrev_b32_e32 v38, 16, v202
	v_and_b32_e32 v39, 0xffff0000, v202
	v_lshlrev_b32_e32 v40, 16, v203
	v_and_b32_e32 v41, 0xffff0000, v203
	v_mul_f32_e32 v24, v24, v99
	v_mul_f32_e32 v25, v25, v99
	v_mul_f32_e32 v26, v26, v99
	v_mul_f32_e32 v27, v27, v99
	v_fmac_f32_e32 v24, v131, v38
	v_fmac_f32_e32 v25, v131, v39
	v_fmac_f32_e32 v26, v131, v40
	v_fmac_f32_e32 v27, v131, v41
	v_cvt_pk_bf16_f32 v28, v24, v25
	v_cvt_pk_bf16_f32 v29, v26, v27
	global_store_dwordx2 v30, v[28:29], s[2:3]
	s_add_u32 s2, s2, 0x20000
	s_addc_u32 s3, s3, 0
	s_waitcnt vmcnt(32)
	v_lshlrev_b32_e32 v38, 16, v204
	v_and_b32_e32 v39, 0xffff0000, v204
	v_lshlrev_b32_e32 v40, 16, v205
	v_and_b32_e32 v41, 0xffff0000, v205
	v_mul_f32_e32 v24, v24, v100
	v_mul_f32_e32 v25, v25, v100
	v_mul_f32_e32 v26, v26, v100
	v_mul_f32_e32 v27, v27, v100
	v_fmac_f32_e32 v24, v132, v38
	v_fmac_f32_e32 v25, v132, v39
	v_fmac_f32_e32 v26, v132, v40
	v_fmac_f32_e32 v27, v132, v41
	v_cvt_pk_bf16_f32 v36, v24, v25
	v_cvt_pk_bf16_f32 v37, v26, v27
	global_store_dwordx2 v30, v[36:37], s[2:3]
	s_add_u32 s2, s2, 0x20000
	s_addc_u32 s3, s3, 0
	s_waitcnt vmcnt(32)
	v_lshlrev_b32_e32 v38, 16, v206
	v_and_b32_e32 v39, 0xffff0000, v206
	v_lshlrev_b32_e32 v40, 16, v207
	v_and_b32_e32 v41, 0xffff0000, v207
	v_mul_f32_e32 v24, v24, v101
	v_mul_f32_e32 v25, v25, v101
	v_mul_f32_e32 v26, v26, v101
	v_mul_f32_e32 v27, v27, v101
	v_fmac_f32_e32 v24, v133, v38
	v_fmac_f32_e32 v25, v133, v39
	v_fmac_f32_e32 v26, v133, v40
	v_fmac_f32_e32 v27, v133, v41
	v_cvt_pk_bf16_f32 v28, v24, v25
	v_cvt_pk_bf16_f32 v29, v26, v27
	global_store_dwordx2 v30, v[28:29], s[2:3]
	s_add_u32 s2, s2, 0x20000
	s_addc_u32 s3, s3, 0
	s_waitcnt vmcnt(32)
	v_lshlrev_b32_e32 v38, 16, v208
	v_and_b32_e32 v39, 0xffff0000, v208
	v_lshlrev_b32_e32 v40, 16, v209
	v_and_b32_e32 v41, 0xffff0000, v209
	v_mul_f32_e32 v24, v24, v102
	v_mul_f32_e32 v25, v25, v102
	v_mul_f32_e32 v26, v26, v102
	v_mul_f32_e32 v27, v27, v102
	v_fmac_f32_e32 v24, v134, v38
	v_fmac_f32_e32 v25, v134, v39
	v_fmac_f32_e32 v26, v134, v40
	v_fmac_f32_e32 v27, v134, v41
	v_cvt_pk_bf16_f32 v36, v24, v25
	v_cvt_pk_bf16_f32 v37, v26, v27
	global_store_dwordx2 v30, v[36:37], s[2:3]
	s_add_u32 s2, s2, 0x20000
	s_addc_u32 s3, s3, 0
	s_waitcnt vmcnt(32)
	v_lshlrev_b32_e32 v38, 16, v210
	v_and_b32_e32 v39, 0xffff0000, v210
	v_lshlrev_b32_e32 v40, 16, v211
	v_and_b32_e32 v41, 0xffff0000, v211
	v_mul_f32_e32 v24, v24, v103
	v_mul_f32_e32 v25, v25, v103
	v_mul_f32_e32 v26, v26, v103
	v_mul_f32_e32 v27, v27, v103
	v_fmac_f32_e32 v24, v135, v38
	v_fmac_f32_e32 v25, v135, v39
	v_fmac_f32_e32 v26, v135, v40
	v_fmac_f32_e32 v27, v135, v41
	v_cvt_pk_bf16_f32 v28, v24, v25
	v_cvt_pk_bf16_f32 v29, v26, v27
	global_store_dwordx2 v30, v[28:29], s[2:3]
	s_add_u32 s2, s2, 0x20000
	s_addc_u32 s3, s3, 0
	s_waitcnt vmcnt(32)
	v_lshlrev_b32_e32 v38, 16, v212
	v_and_b32_e32 v39, 0xffff0000, v212
	v_lshlrev_b32_e32 v40, 16, v213
	v_and_b32_e32 v41, 0xffff0000, v213
	v_mul_f32_e32 v24, v24, v104
	v_mul_f32_e32 v25, v25, v104
	v_mul_f32_e32 v26, v26, v104
	v_mul_f32_e32 v27, v27, v104
	v_fmac_f32_e32 v24, v136, v38
	v_fmac_f32_e32 v25, v136, v39
	v_fmac_f32_e32 v26, v136, v40
	v_fmac_f32_e32 v27, v136, v41
	v_cvt_pk_bf16_f32 v36, v24, v25
	v_cvt_pk_bf16_f32 v37, v26, v27
	global_store_dwordx2 v30, v[36:37], s[2:3]
	s_add_u32 s2, s2, 0x20000
	s_addc_u32 s3, s3, 0
	s_waitcnt vmcnt(32)
	v_lshlrev_b32_e32 v38, 16, v214
	v_and_b32_e32 v39, 0xffff0000, v214
	v_lshlrev_b32_e32 v40, 16, v215
	v_and_b32_e32 v41, 0xffff0000, v215
	v_mul_f32_e32 v24, v24, v105
	v_mul_f32_e32 v25, v25, v105
	v_mul_f32_e32 v26, v26, v105
	v_mul_f32_e32 v27, v27, v105
	v_fmac_f32_e32 v24, v137, v38
	v_fmac_f32_e32 v25, v137, v39
	v_fmac_f32_e32 v26, v137, v40
	v_fmac_f32_e32 v27, v137, v41
	v_cvt_pk_bf16_f32 v28, v24, v25
	v_cvt_pk_bf16_f32 v29, v26, v27
	global_store_dwordx2 v30, v[28:29], s[2:3]
	s_add_u32 s2, s2, 0x20000
	s_addc_u32 s3, s3, 0
	s_waitcnt vmcnt(32)
	v_lshlrev_b32_e32 v38, 16, v216
	v_and_b32_e32 v39, 0xffff0000, v216
	v_lshlrev_b32_e32 v40, 16, v217
	v_and_b32_e32 v41, 0xffff0000, v217
	v_mul_f32_e32 v24, v24, v106
	v_mul_f32_e32 v25, v25, v106
	v_mul_f32_e32 v26, v26, v106
	v_mul_f32_e32 v27, v27, v106
	v_fmac_f32_e32 v24, v138, v38
	v_fmac_f32_e32 v25, v138, v39
	v_fmac_f32_e32 v26, v138, v40
	v_fmac_f32_e32 v27, v138, v41
	v_cvt_pk_bf16_f32 v36, v24, v25
	v_cvt_pk_bf16_f32 v37, v26, v27
	global_store_dwordx2 v30, v[36:37], s[2:3]
	s_add_u32 s2, s2, 0x20000
	s_addc_u32 s3, s3, 0
	s_waitcnt vmcnt(32)
	v_lshlrev_b32_e32 v38, 16, v218
	v_and_b32_e32 v39, 0xffff0000, v218
	v_lshlrev_b32_e32 v40, 16, v219
	v_and_b32_e32 v41, 0xffff0000, v219
	v_mul_f32_e32 v24, v24, v107
	v_mul_f32_e32 v25, v25, v107
	v_mul_f32_e32 v26, v26, v107
	v_mul_f32_e32 v27, v27, v107
	v_fmac_f32_e32 v24, v139, v38
	v_fmac_f32_e32 v25, v139, v39
	v_fmac_f32_e32 v26, v139, v40
	v_fmac_f32_e32 v27, v139, v41
	v_cvt_pk_bf16_f32 v28, v24, v25
	v_cvt_pk_bf16_f32 v29, v26, v27
	global_store_dwordx2 v30, v[28:29], s[2:3]
	s_add_u32 s2, s2, 0x20000
	s_addc_u32 s3, s3, 0
	s_waitcnt vmcnt(32)
	v_lshlrev_b32_e32 v38, 16, v220
	v_and_b32_e32 v39, 0xffff0000, v220
	v_lshlrev_b32_e32 v40, 16, v221
	v_and_b32_e32 v41, 0xffff0000, v221
	v_mul_f32_e32 v24, v24, v108
	v_mul_f32_e32 v25, v25, v108
	v_mul_f32_e32 v26, v26, v108
	v_mul_f32_e32 v27, v27, v108
	v_fmac_f32_e32 v24, v140, v38
	v_fmac_f32_e32 v25, v140, v39
	v_fmac_f32_e32 v26, v140, v40
	v_fmac_f32_e32 v27, v140, v41
	v_cvt_pk_bf16_f32 v36, v24, v25
	v_cvt_pk_bf16_f32 v37, v26, v27
	global_store_dwordx2 v30, v[36:37], s[2:3]
	s_add_u32 s2, s2, 0x20000
	s_addc_u32 s3, s3, 0
	s_waitcnt vmcnt(32)
	v_lshlrev_b32_e32 v38, 16, v222
	v_and_b32_e32 v39, 0xffff0000, v222
	v_lshlrev_b32_e32 v40, 16, v223
	v_and_b32_e32 v41, 0xffff0000, v223
	v_mul_f32_e32 v24, v24, v109
	v_mul_f32_e32 v25, v25, v109
	v_mul_f32_e32 v26, v26, v109
	v_mul_f32_e32 v27, v27, v109
	v_fmac_f32_e32 v24, v141, v38
	v_fmac_f32_e32 v25, v141, v39
	v_fmac_f32_e32 v26, v141, v40
	v_fmac_f32_e32 v27, v141, v41
	v_cvt_pk_bf16_f32 v28, v24, v25
	v_cvt_pk_bf16_f32 v29, v26, v27
	global_store_dwordx2 v30, v[28:29], s[2:3]
	s_add_u32 s2, s2, 0x20000
	s_addc_u32 s3, s3, 0
	s_waitcnt vmcnt(32)
	v_lshlrev_b32_e32 v38, 16, v224
	v_and_b32_e32 v39, 0xffff0000, v224
	v_lshlrev_b32_e32 v40, 16, v225
	v_and_b32_e32 v41, 0xffff0000, v225
	v_mul_f32_e32 v24, v24, v110
	v_mul_f32_e32 v25, v25, v110
	v_mul_f32_e32 v26, v26, v110
	v_mul_f32_e32 v27, v27, v110
	v_fmac_f32_e32 v24, v142, v38
	v_fmac_f32_e32 v25, v142, v39
	v_fmac_f32_e32 v26, v142, v40
	v_fmac_f32_e32 v27, v142, v41
	v_cvt_pk_bf16_f32 v36, v24, v25
	v_cvt_pk_bf16_f32 v37, v26, v27
	global_store_dwordx2 v30, v[36:37], s[2:3]
	s_add_u32 s2, s2, 0x20000
	s_addc_u32 s3, s3, 0
	s_waitcnt vmcnt(32)
	v_lshlrev_b32_e32 v38, 16, v226
	v_and_b32_e32 v39, 0xffff0000, v226
	v_lshlrev_b32_e32 v40, 16, v227
	v_and_b32_e32 v41, 0xffff0000, v227
	v_mul_f32_e32 v24, v24, v111
	v_mul_f32_e32 v25, v25, v111
	v_mul_f32_e32 v26, v26, v111
	v_mul_f32_e32 v27, v27, v111
	v_fmac_f32_e32 v24, v143, v38
	v_fmac_f32_e32 v25, v143, v39
	v_fmac_f32_e32 v26, v143, v40
	v_fmac_f32_e32 v27, v143, v41
	v_cvt_pk_bf16_f32 v28, v24, v25
	v_cvt_pk_bf16_f32 v29, v26, v27
	global_store_dwordx2 v30, v[28:29], s[2:3]
	s_add_u32 s2, s2, 0x20000
	s_addc_u32 s3, s3, 0
	s_waitcnt vmcnt(32)
	v_lshlrev_b32_e32 v38, 16, v228
	v_and_b32_e32 v39, 0xffff0000, v228
	v_lshlrev_b32_e32 v40, 16, v229
	v_and_b32_e32 v41, 0xffff0000, v229
	v_mul_f32_e32 v24, v24, v112
	v_mul_f32_e32 v25, v25, v112
	v_mul_f32_e32 v26, v26, v112
	v_mul_f32_e32 v27, v27, v112
	v_fmac_f32_e32 v24, v144, v38
	v_fmac_f32_e32 v25, v144, v39
	v_fmac_f32_e32 v26, v144, v40
	v_fmac_f32_e32 v27, v144, v41
	v_cvt_pk_bf16_f32 v36, v24, v25
	v_cvt_pk_bf16_f32 v37, v26, v27
	global_store_dwordx2 v30, v[36:37], s[2:3]
	s_add_u32 s2, s2, 0x20000
	s_addc_u32 s3, s3, 0
	s_waitcnt vmcnt(32)
	v_lshlrev_b32_e32 v38, 16, v230
	v_and_b32_e32 v39, 0xffff0000, v230
	v_lshlrev_b32_e32 v40, 16, v231
	v_and_b32_e32 v41, 0xffff0000, v231
	v_mul_f32_e32 v24, v24, v113
	v_mul_f32_e32 v25, v25, v113
	v_mul_f32_e32 v26, v26, v113
	v_mul_f32_e32 v27, v27, v113
	v_fmac_f32_e32 v24, v145, v38
	v_fmac_f32_e32 v25, v145, v39
	v_fmac_f32_e32 v26, v145, v40
	v_fmac_f32_e32 v27, v145, v41
	v_cvt_pk_bf16_f32 v28, v24, v25
	v_cvt_pk_bf16_f32 v29, v26, v27
	global_store_dwordx2 v30, v[28:29], s[2:3]
	s_add_u32 s2, s2, 0x20000
	s_addc_u32 s3, s3, 0
	s_waitcnt vmcnt(32)
	v_lshlrev_b32_e32 v38, 16, v232
	v_and_b32_e32 v39, 0xffff0000, v232
	v_lshlrev_b32_e32 v40, 16, v233
	v_and_b32_e32 v41, 0xffff0000, v233
	v_mul_f32_e32 v24, v24, v114
	v_mul_f32_e32 v25, v25, v114
	v_mul_f32_e32 v26, v26, v114
	v_mul_f32_e32 v27, v27, v114
	v_fmac_f32_e32 v24, v146, v38
	v_fmac_f32_e32 v25, v146, v39
	v_fmac_f32_e32 v26, v146, v40
	v_fmac_f32_e32 v27, v146, v41
	v_cvt_pk_bf16_f32 v36, v24, v25
	v_cvt_pk_bf16_f32 v37, v26, v27
	global_store_dwordx2 v30, v[36:37], s[2:3]
	s_add_u32 s2, s2, 0x20000
	s_addc_u32 s3, s3, 0
	s_waitcnt vmcnt(32)
	v_lshlrev_b32_e32 v38, 16, v234
	v_and_b32_e32 v39, 0xffff0000, v234
	v_lshlrev_b32_e32 v40, 16, v235
	v_and_b32_e32 v41, 0xffff0000, v235
	v_mul_f32_e32 v24, v24, v115
	v_mul_f32_e32 v25, v25, v115
	v_mul_f32_e32 v26, v26, v115
	v_mul_f32_e32 v27, v27, v115
	v_fmac_f32_e32 v24, v147, v38
	v_fmac_f32_e32 v25, v147, v39
	v_fmac_f32_e32 v26, v147, v40
	v_fmac_f32_e32 v27, v147, v41
	v_cvt_pk_bf16_f32 v28, v24, v25
	v_cvt_pk_bf16_f32 v29, v26, v27
	global_store_dwordx2 v30, v[28:29], s[2:3]
	s_add_u32 s2, s2, 0x20000
	s_addc_u32 s3, s3, 0
	s_waitcnt vmcnt(32)
	v_lshlrev_b32_e32 v38, 16, v236
	v_and_b32_e32 v39, 0xffff0000, v236
	v_lshlrev_b32_e32 v40, 16, v237
	v_and_b32_e32 v41, 0xffff0000, v237
	v_mul_f32_e32 v24, v24, v116
	v_mul_f32_e32 v25, v25, v116
	v_mul_f32_e32 v26, v26, v116
	v_mul_f32_e32 v27, v27, v116
	v_fmac_f32_e32 v24, v148, v38
	v_fmac_f32_e32 v25, v148, v39
	v_fmac_f32_e32 v26, v148, v40
	v_fmac_f32_e32 v27, v148, v41
	v_cvt_pk_bf16_f32 v36, v24, v25
	v_cvt_pk_bf16_f32 v37, v26, v27
	global_store_dwordx2 v30, v[36:37], s[2:3]
	s_add_u32 s2, s2, 0x20000
	s_addc_u32 s3, s3, 0
	s_waitcnt vmcnt(32)
	v_lshlrev_b32_e32 v38, 16, v238
	v_and_b32_e32 v39, 0xffff0000, v238
	v_lshlrev_b32_e32 v40, 16, v239
	v_and_b32_e32 v41, 0xffff0000, v239
	v_mul_f32_e32 v24, v24, v117
	v_mul_f32_e32 v25, v25, v117
	v_mul_f32_e32 v26, v26, v117
	v_mul_f32_e32 v27, v27, v117
	v_fmac_f32_e32 v24, v149, v38
	v_fmac_f32_e32 v25, v149, v39
	v_fmac_f32_e32 v26, v149, v40
	v_fmac_f32_e32 v27, v149, v41
	v_cvt_pk_bf16_f32 v28, v24, v25
	v_cvt_pk_bf16_f32 v29, v26, v27
	global_store_dwordx2 v30, v[28:29], s[2:3]
	s_add_u32 s2, s2, 0x20000
	s_addc_u32 s3, s3, 0
	s_waitcnt vmcnt(32)
	v_lshlrev_b32_e32 v38, 16, v240
	v_and_b32_e32 v39, 0xffff0000, v240
	v_lshlrev_b32_e32 v40, 16, v241
	v_and_b32_e32 v41, 0xffff0000, v241
	v_mul_f32_e32 v24, v24, v118
	v_mul_f32_e32 v25, v25, v118
	v_mul_f32_e32 v26, v26, v118
	v_mul_f32_e32 v27, v27, v118
	v_fmac_f32_e32 v24, v150, v38
	v_fmac_f32_e32 v25, v150, v39
	v_fmac_f32_e32 v26, v150, v40
	v_fmac_f32_e32 v27, v150, v41
	v_cvt_pk_bf16_f32 v36, v24, v25
	v_cvt_pk_bf16_f32 v37, v26, v27
	global_store_dwordx2 v30, v[36:37], s[2:3]
	s_add_u32 s2, s2, 0x20000
	s_addc_u32 s3, s3, 0
	s_waitcnt vmcnt(32)
	v_lshlrev_b32_e32 v38, 16, v242
	v_and_b32_e32 v39, 0xffff0000, v242
	v_lshlrev_b32_e32 v40, 16, v243
	v_and_b32_e32 v41, 0xffff0000, v243
	v_mul_f32_e32 v24, v24, v119
	v_mul_f32_e32 v25, v25, v119
	v_mul_f32_e32 v26, v26, v119
	v_mul_f32_e32 v27, v27, v119
	v_fmac_f32_e32 v24, v151, v38
	v_fmac_f32_e32 v25, v151, v39
	v_fmac_f32_e32 v26, v151, v40
	v_fmac_f32_e32 v27, v151, v41
	v_cvt_pk_bf16_f32 v28, v24, v25
	v_cvt_pk_bf16_f32 v29, v26, v27
	global_store_dwordx2 v30, v[28:29], s[2:3]
	s_add_u32 s2, s2, 0x20000
	s_addc_u32 s3, s3, 0
	s_waitcnt vmcnt(32)
	v_lshlrev_b32_e32 v38, 16, v244
	v_and_b32_e32 v39, 0xffff0000, v244
	v_lshlrev_b32_e32 v40, 16, v245
	v_and_b32_e32 v41, 0xffff0000, v245
	v_mul_f32_e32 v24, v24, v120
	v_mul_f32_e32 v25, v25, v120
	v_mul_f32_e32 v26, v26, v120
	v_mul_f32_e32 v27, v27, v120
	v_fmac_f32_e32 v24, v152, v38
	v_fmac_f32_e32 v25, v152, v39
	v_fmac_f32_e32 v26, v152, v40
	v_fmac_f32_e32 v27, v152, v41
	v_cvt_pk_bf16_f32 v36, v24, v25
	v_cvt_pk_bf16_f32 v37, v26, v27
	global_store_dwordx2 v30, v[36:37], s[2:3]
	s_waitcnt vmcnt(32)
	v_lshlrev_b32_e32 v38, 16, v246
	v_and_b32_e32 v39, 0xffff0000, v246
	v_lshlrev_b32_e32 v40, 16, v247
	v_and_b32_e32 v41, 0xffff0000, v247
	v_mul_f32_e32 v24, v24, v121
	v_mul_f32_e32 v25, v25, v121
	v_mul_f32_e32 v26, v26, v121
	v_mul_f32_e32 v27, v27, v121
	v_fmac_f32_e32 v24, v153, v38
	v_fmac_f32_e32 v25, v153, v39
	v_fmac_f32_e32 v26, v153, v40
	v_fmac_f32_e32 v27, v153, v41
	v_cmp_eq_u32_e32 vcc, 0, v30
	s_and_saveexec_b64 s[14:15], vcc
	s_cbranch_execz .Ld3_nomk
	s_add_u32 s10, s10, 0x2000
	s_addc_u32 s11, s11, 0
	v_mov_b32_e32 v29, 0
	global_store_dword v29, v49, s[10:11] offset:0
	global_store_dword v29, v50, s[10:11] offset:4
	global_store_dword v29, v51, s[10:11] offset:8
	global_store_dword v29, v52, s[10:11] offset:12
	global_store_dword v29, v53, s[10:11] offset:16
	global_store_dword v29, v54, s[10:11] offset:20
	global_store_dword v29, v55, s[10:11] offset:24
	global_store_dword v29, v56, s[10:11] offset:28
	global_store_dword v29, v57, s[10:11] offset:32
	global_store_dword v29, v58, s[10:11] offset:36
	global_store_dword v29, v59, s[10:11] offset:40
	global_store_dword v29, v60, s[10:11] offset:44
	global_store_dword v29, v61, s[10:11] offset:48
	global_store_dword v29, v62, s[10:11] offset:52
	global_store_dword v29, v63, s[10:11] offset:56
	global_store_dword v29, v64, s[10:11] offset:60
	global_store_dword v29, v65, s[10:11] offset:64
	global_store_dword v29, v66, s[10:11] offset:68
	global_store_dword v29, v67, s[10:11] offset:72
	global_store_dword v29, v68, s[10:11] offset:76
	global_store_dword v29, v69, s[10:11] offset:80
	global_store_dword v29, v70, s[10:11] offset:84
	global_store_dword v29, v71, s[10:11] offset:88
	global_store_dword v29, v72, s[10:11] offset:92
	global_store_dword v29, v73, s[10:11] offset:96
	global_store_dword v29, v74, s[10:11] offset:100
	global_store_dword v29, v75, s[10:11] offset:104
	global_store_dword v29, v76, s[10:11] offset:108
	global_store_dword v29, v77, s[10:11] offset:112
	global_store_dword v29, v78, s[10:11] offset:116
	global_store_dword v29, v79, s[10:11] offset:120
	global_store_dword v29, v80, s[10:11] offset:124
.Ld3_nomk:
	s_or_b64 exec, exec, s[14:15]
	s_add_u32 s6, s6, s66
	s_branch .Ld3_loop
.Ld3_part2:
	s_mov_b32 s6, s67
.Ld3_p2loop:
	s_cmp_lt_u32 s6, 0x800
	s_cbranch_scc0 .Ld3_done
	v_add_u32_e32 v30, s6, v182
	v_lshrrev_b32_e32 v31, 8, v30
	v_and_b32_e32 v32, 0xff, v30
	v_lshlrev_b32_e32 v33, 7, v31
	s_add_u32 s10, s58, 0x340000
	s_addc_u32 s11, s59, 0
	s_add_u32 s12, s58, 0x341000
	s_addc_u32 s13, s59, 0
	global_load_dwordx4 v[90:93], v33, s[10:11] offset:0
	global_load_dwordx4 v[94:97], v33, s[10:11] offset:16
	global_load_dwordx4 v[98:101], v33, s[10:11] offset:32
	global_load_dwordx4 v[102:105], v33, s[10:11] offset:48
	global_load_dwordx4 v[106:109], v33, s[10:11] offset:64
	global_load_dwordx4 v[110:113], v33, s[10:11] offset:80
	global_load_dwordx4 v[114:117], v33, s[10:11] offset:96
	global_load_dwordx4 v[118:121], v33, s[10:11] offset:112
	global_load_dwordx4 v[122:125], v33, s[12:13] offset:0
	global_load_dwordx4 v[126:129], v33, s[12:13] offset:16
	global_load_dwordx4 v[130:133], v33, s[12:13] offset:32
	global_load_dwordx4 v[134:137], v33, s[12:13] offset:48
	global_load_dwordx4 v[138:141], v33, s[12:13] offset:64
	global_load_dwordx4 v[142:145], v33, s[12:13] offset:80
	global_load_dwordx4 v[146:149], v33, s[12:13] offset:96
	global_load_dwordx4 v[150:153], v33, s[12:13] offset:112
	v_lshlrev_b32_e32 v34, 15, v31
	v_lshl_add_u32 v34, v32, 2, v34
	s_add_u32 s0, s58, 0x380000
	s_addc_u32 s1, s59, 0
	global_load_dword v184, v34, s[0:1] offset:0
	global_load_dword v185, v34, s[0:1] offset:1024
	global_load_dword v186, v34, s[0:1] offset:2048
	global_load_dword v187, v34, s[0:1] offset:3072
	s_add_u32 s0, s0, 0x1000
	s_addc_u32 s1, s1, 0
	global_load_dword v188, v34, s[0:1] offset:0
	global_load_dword v189, v34, s[0:1] offset:1024
	global_load_dword v190, v34, s[0:1] offset:2048
	global_load_dword v191, v34, s[0:1] offset:3072
	s_add_u32 s0, s0, 0x1000
	s_addc_u32 s1, s1, 0
	global_load_dword v192, v34, s[0:1] offset:0
	global_load_dword v193, v34, s[0:1] offset:1024
	global_load_dword v194, v34, s[0:1] offset:2048
	global_load_dword v195, v34, s[0:1] offset:3072
	s_add_u32 s0, s0, 0x1000
	s_addc_u32 s1, s1, 0
	global_load_dword v196, v34, s[0:1] offset:0
	global_load_dword v197, v34, s[0:1] offset:1024
	global_load_dword v198, v34, s[0:1] offset:2048
	global_load_dword v199, v34, s[0:1] offset:3072
	s_add_u32 s0, s0, 0x1000
	s_addc_u32 s1, s1, 0
	global_load_dword v200, v34, s[0:1] offset:0
	global_load_dword v201, v34, s[0:1] offset:1024
	global_load_dword v202, v34, s[0:1] offset:2048
	global_load_dword v203, v34, s[0:1] offset:3072
	s_add_u32 s0, s0, 0x1000
	s_addc_u32 s1, s1, 0
	global_load_dword v204, v34, s[0:1] offset:0
	global_load_dword v205, v34, s[0:1] offset:1024
	global_load_dword v206, v34, s[0:1] offset:2048
	global_load_dword v207, v34, s[0:1] offset:3072
	s_add_u32 s0, s0, 0x1000
	s_addc_u32 s1, s1, 0
	global_load_dword v208, v34, s[0:1] offset:0
	global_load_dword v209, v34, s[0:1] offset:1024
	global_load_dword v210, v34, s[0:1] offset:2048
	global_load_dword v211, v34, s[0:1] offset:3072
	s_add_u32 s0, s0, 0x1000
	s_addc_u32 s1, s1, 0
	global_load_dword v212, v34, s[0:1] offset:0
	global_load_dword v213, v34, s[0:1] offset:1024
	global_load_dword v214, v34, s[0:1] offset:2048
	global_load_dword v215, v34, s[0:1] offset:3072
	s_add_u32 s2, s58, 0x3c0000
	s_addc_u32 s3, s59, 0
	s_waitcnt vmcnt(32)
	v_mov_b32_e32 v35, 0
	v_mov_b32_e32 v49, v35
	v_add_f32_e32 v90, v35, v90
	v_max_f32_e32 v36, v122, v122
	v_max_f32_e32 v35, v90, v36
	v_sub_f32_e32 v90, v90, v35
	v_sub_f32_e32 v122, v122, v35
	v_mul_f32_e32 v90, 0x3fb8aa3b, v90
	v_mul_f32_e32 v122, 0x3fb8aa3b, v122
	v_exp_f32_e32 v90, v90
	v_exp_f32_e32 v122, v122
	v_mov_b32_e32 v50, v35
	v_add_f32_e32 v91, v35, v91
	v_max_f32_e32 v36, v123, v123
	v_max_f32_e32 v35, v91, v36
	v_sub_f32_e32 v91, v91, v35
	v_sub_f32_e32 v123, v123, v35
	v_mul_f32_e32 v91, 0x3fb8aa3b, v91
	v_mul_f32_e32 v123, 0x3fb8aa3b, v123
	v_exp_f32_e32 v91, v91
	v_exp_f32_e32 v123, v123
	v_mov_b32_e32 v51, v35
	v_add_f32_e32 v92, v35, v92
	v_max_f32_e32 v36, v124, v124
	v_max_f32_e32 v35, v92, v36
	v_sub_f32_e32 v92, v92, v35
	v_sub_f32_e32 v124, v124, v35
	v_mul_f32_e32 v92, 0x3fb8aa3b, v92
	v_mul_f32_e32 v124, 0x3fb8aa3b, v124
	v_exp_f32_e32 v92, v92
	v_exp_f32_e32 v124, v124
	v_mov_b32_e32 v52, v35
	v_add_f32_e32 v93, v35, v93
	v_max_f32_e32 v36, v125, v125
	v_max_f32_e32 v35, v93, v36
	v_sub_f32_e32 v93, v93, v35
	v_sub_f32_e32 v125, v125, v35
	v_mul_f32_e32 v93, 0x3fb8aa3b, v93
	v_mul_f32_e32 v125, 0x3fb8aa3b, v125
	v_exp_f32_e32 v93, v93
	v_exp_f32_e32 v125, v125
	v_mov_b32_e32 v53, v35
	v_add_f32_e32 v94, v35, v94
	v_max_f32_e32 v36, v126, v126
	v_max_f32_e32 v35, v94, v36
	v_sub_f32_e32 v94, v94, v35
	v_sub_f32_e32 v126, v126, v35
	v_mul_f32_e32 v94, 0x3fb8aa3b, v94
	v_mul_f32_e32 v126, 0x3fb8aa3b, v126
	v_exp_f32_e32 v94, v94
	v_exp_f32_e32 v126, v126
	v_mov_b32_e32 v54, v35
	v_add_f32_e32 v95, v35, v95
	v_max_f32_e32 v36, v127, v127
	v_max_f32_e32 v35, v95, v36
	v_sub_f32_e32 v95, v95, v35
	v_sub_f32_e32 v127, v127, v35
	v_mul_f32_e32 v95, 0x3fb8aa3b, v95
	v_mul_f32_e32 v127, 0x3fb8aa3b, v127
	v_exp_f32_e32 v95, v95
	v_exp_f32_e32 v127, v127
	v_mov_b32_e32 v55, v35
	v_add_f32_e32 v96, v35, v96
	v_max_f32_e32 v36, v128, v128
	v_max_f32_e32 v35, v96, v36
	v_sub_f32_e32 v96, v96, v35
	v_sub_f32_e32 v128, v128, v35
	v_mul_f32_e32 v96, 0x3fb8aa3b, v96
	v_mul_f32_e32 v128, 0x3fb8aa3b, v128
	v_exp_f32_e32 v96, v96
	v_exp_f32_e32 v128, v128
	v_mov_b32_e32 v56, v35
	v_add_f32_e32 v97, v35, v97
	v_max_f32_e32 v36, v129, v129
	v_max_f32_e32 v35, v97, v36
	v_sub_f32_e32 v97, v97, v35
	v_sub_f32_e32 v129, v129, v35
	v_mul_f32_e32 v97, 0x3fb8aa3b, v97
	v_mul_f32_e32 v129, 0x3fb8aa3b, v129
	v_exp_f32_e32 v97, v97
	v_exp_f32_e32 v129, v129
	v_mov_b32_e32 v57, v35
	v_add_f32_e32 v98, v35, v98
	v_max_f32_e32 v36, v130, v130
	v_max_f32_e32 v35, v98, v36
	v_sub_f32_e32 v98, v98, v35
	v_sub_f32_e32 v130, v130, v35
	v_mul_f32_e32 v98, 0x3fb8aa3b, v98
	v_mul_f32_e32 v130, 0x3fb8aa3b, v130
	v_exp_f32_e32 v98, v98
	v_exp_f32_e32 v130, v130
	v_mov_b32_e32 v58, v35
	v_add_f32_e32 v99, v35, v99
	v_max_f32_e32 v36, v131, v131
	v_max_f32_e32 v35, v99, v36
	v_sub_f32_e32 v99, v99, v35
	v_sub_f32_e32 v131, v131, v35
	v_mul_f32_e32 v99, 0x3fb8aa3b, v99
	v_mul_f32_e32 v131, 0x3fb8aa3b, v131
	v_exp_f32_e32 v99, v99
	v_exp_f32_e32 v131, v131
	v_mov_b32_e32 v59, v35
	v_add_f32_e32 v100, v35, v100
	v_max_f32_e32 v36, v132, v132
	v_max_f32_e32 v35, v100, v36
	v_sub_f32_e32 v100, v100, v35
	v_sub_f32_e32 v132, v132, v35
	v_mul_f32_e32 v100, 0x3fb8aa3b, v100
	v_mul_f32_e32 v132, 0x3fb8aa3b, v132
	v_exp_f32_e32 v100, v100
	v_exp_f32_e32 v132, v132
	v_mov_b32_e32 v60, v35
	v_add_f32_e32 v101, v35, v101
	v_max_f32_e32 v36, v133, v133
	v_max_f32_e32 v35, v101, v36
	v_sub_f32_e32 v101, v101, v35
	v_sub_f32_e32 v133, v133, v35
	v_mul_f32_e32 v101, 0x3fb8aa3b, v101
	v_mul_f32_e32 v133, 0x3fb8aa3b, v133
	v_exp_f32_e32 v101, v101
	v_exp_f32_e32 v133, v133
	v_mov_b32_e32 v61, v35
	v_add_f32_e32 v102, v35, v102
	v_max_f32_e32 v36, v134, v134
	v_max_f32_e32 v35, v102, v36
	v_sub_f32_e32 v102, v102, v35
	v_sub_f32_e32 v134, v134, v35
	v_mul_f32_e32 v102, 0x3fb8aa3b, v102
	v_mul_f32_e32 v134, 0x3fb8aa3b, v134
	v_exp_f32_e32 v102, v102
	v_exp_f32_e32 v134, v134
	v_mov_b32_e32 v62, v35
	v_add_f32_e32 v103, v35, v103
	v_max_f32_e32 v36, v135, v135
	v_max_f32_e32 v35, v103, v36
	v_sub_f32_e32 v103, v103, v35
	v_sub_f32_e32 v135, v135, v35
	v_mul_f32_e32 v103, 0x3fb8aa3b, v103
	v_mul_f32_e32 v135, 0x3fb8aa3b, v135
	v_exp_f32_e32 v103, v103
	v_exp_f32_e32 v135, v135
	v_mov_b32_e32 v63, v35
	v_add_f32_e32 v104, v35, v104
	v_max_f32_e32 v36, v136, v136
	v_max_f32_e32 v35, v104, v36
	v_sub_f32_e32 v104, v104, v35
	v_sub_f32_e32 v136, v136, v35
	v_mul_f32_e32 v104, 0x3fb8aa3b, v104
	v_mul_f32_e32 v136, 0x3fb8aa3b, v136
	v_exp_f32_e32 v104, v104
	v_exp_f32_e32 v136, v136
	v_mov_b32_e32 v64, v35
	v_add_f32_e32 v105, v35, v105
	v_max_f32_e32 v36, v137, v137
	v_max_f32_e32 v35, v105, v36
	v_sub_f32_e32 v105, v105, v35
	v_sub_f32_e32 v137, v137, v35
	v_mul_f32_e32 v105, 0x3fb8aa3b, v105
	v_mul_f32_e32 v137, 0x3fb8aa3b, v137
	v_exp_f32_e32 v105, v105
	v_exp_f32_e32 v137, v137
	v_mov_b32_e32 v65, v35
	v_add_f32_e32 v106, v35, v106
	v_max_f32_e32 v36, v138, v138
	v_max_f32_e32 v35, v106, v36
	v_sub_f32_e32 v106, v106, v35
	v_sub_f32_e32 v138, v138, v35
	v_mul_f32_e32 v106, 0x3fb8aa3b, v106
	v_mul_f32_e32 v138, 0x3fb8aa3b, v138
	v_exp_f32_e32 v106, v106
	v_exp_f32_e32 v138, v138
	v_mov_b32_e32 v66, v35
	v_add_f32_e32 v107, v35, v107
	v_max_f32_e32 v36, v139, v139
	v_max_f32_e32 v35, v107, v36
	v_sub_f32_e32 v107, v107, v35
	v_sub_f32_e32 v139, v139, v35
	v_mul_f32_e32 v107, 0x3fb8aa3b, v107
	v_mul_f32_e32 v139, 0x3fb8aa3b, v139
	v_exp_f32_e32 v107, v107
	v_exp_f32_e32 v139, v139
	v_mov_b32_e32 v67, v35
	v_add_f32_e32 v108, v35, v108
	v_max_f32_e32 v36, v140, v140
	v_max_f32_e32 v35, v108, v36
	v_sub_f32_e32 v108, v108, v35
	v_sub_f32_e32 v140, v140, v35
	v_mul_f32_e32 v108, 0x3fb8aa3b, v108
	v_mul_f32_e32 v140, 0x3fb8aa3b, v140
	v_exp_f32_e32 v108, v108
	v_exp_f32_e32 v140, v140
	v_mov_b32_e32 v68, v35
	v_add_f32_e32 v109, v35, v109
	v_max_f32_e32 v36, v141, v141
	v_max_f32_e32 v35, v109, v36
	v_sub_f32_e32 v109, v109, v35
	v_sub_f32_e32 v141, v141, v35
	v_mul_f32_e32 v109, 0x3fb8aa3b, v109
	v_mul_f32_e32 v141, 0x3fb8aa3b, v141
	v_exp_f32_e32 v109, v109
	v_exp_f32_e32 v141, v141
	v_mov_b32_e32 v69, v35
	v_add_f32_e32 v110, v35, v110
	v_max_f32_e32 v36, v142, v142
	v_max_f32_e32 v35, v110, v36
	v_sub_f32_e32 v110, v110, v35
	v_sub_f32_e32 v142, v142, v35
	v_mul_f32_e32 v110, 0x3fb8aa3b, v110
	v_mul_f32_e32 v142, 0x3fb8aa3b, v142
	v_exp_f32_e32 v110, v110
	v_exp_f32_e32 v142, v142
	v_mov_b32_e32 v70, v35
	v_add_f32_e32 v111, v35, v111
	v_max_f32_e32 v36, v143, v143
	v_max_f32_e32 v35, v111, v36
	v_sub_f32_e32 v111, v111, v35
	v_sub_f32_e32 v143, v143, v35
	v_mul_f32_e32 v111, 0x3fb8aa3b, v111
	v_mul_f32_e32 v143, 0x3fb8aa3b, v143
	v_exp_f32_e32 v111, v111
	v_exp_f32_e32 v143, v143
	v_mov_b32_e32 v71, v35
	v_add_f32_e32 v112, v35, v112
	v_max_f32_e32 v36, v144, v144
	v_max_f32_e32 v35, v112, v36
	v_sub_f32_e32 v112, v112, v35
	v_sub_f32_e32 v144, v144, v35
	v_mul_f32_e32 v112, 0x3fb8aa3b, v112
	v_mul_f32_e32 v144, 0x3fb8aa3b, v144
	v_exp_f32_e32 v112, v112
	v_exp_f32_e32 v144, v144
	v_mov_b32_e32 v72, v35
	v_add_f32_e32 v113, v35, v113
	v_max_f32_e32 v36, v145, v145
	v_max_f32_e32 v35, v113, v36
	v_sub_f32_e32 v113, v113, v35
	v_sub_f32_e32 v145, v145, v35
	v_mul_f32_e32 v113, 0x3fb8aa3b, v113
	v_mul_f32_e32 v145, 0x3fb8aa3b, v145
	v_exp_f32_e32 v113, v113
	v_exp_f32_e32 v145, v145
	v_mov_b32_e32 v73, v35
	v_add_f32_e32 v114, v35, v114
	v_max_f32_e32 v36, v146, v146
	v_max_f32_e32 v35, v114, v36
	v_sub_f32_e32 v114, v114, v35
	v_sub_f32_e32 v146, v146, v35
	v_mul_f32_e32 v114, 0x3fb8aa3b, v114
	v_mul_f32_e32 v146, 0x3fb8aa3b, v146
	v_exp_f32_e32 v114, v114
	v_exp_f32_e32 v146, v146
	v_mov_b32_e32 v74, v35
	v_add_f32_e32 v115, v35, v115
	v_max_f32_e32 v36, v147, v147
	v_max_f32_e32 v35, v115, v36
	v_sub_f32_e32 v115, v115, v35
	v_sub_f32_e32 v147, v147, v35
	v_mul_f32_e32 v115, 0x3fb8aa3b, v115
	v_mul_f32_e32 v147, 0x3fb8aa3b, v147
	v_exp_f32_e32 v115, v115
	v_exp_f32_e32 v147, v147
	v_mov_b32_e32 v75, v35
	v_add_f32_e32 v116, v35, v116
	v_max_f32_e32 v36, v148, v148
	v_max_f32_e32 v35, v116, v36
	v_sub_f32_e32 v116, v116, v35
	v_sub_f32_e32 v148, v148, v35
	v_mul_f32_e32 v116, 0x3fb8aa3b, v116
	v_mul_f32_e32 v148, 0x3fb8aa3b, v148
	v_exp_f32_e32 v116, v116
	v_exp_f32_e32 v148, v148
	v_mov_b32_e32 v76, v35
	v_add_f32_e32 v117, v35, v117
	v_max_f32_e32 v36, v149, v149
	v_max_f32_e32 v35, v117, v36
	v_sub_f32_e32 v117, v117, v35
	v_sub_f32_e32 v149, v149, v35
	v_mul_f32_e32 v117, 0x3fb8aa3b, v117
	v_mul_f32_e32 v149, 0x3fb8aa3b, v149
	v_exp_f32_e32 v117, v117
	v_exp_f32_e32 v149, v149
	v_mov_b32_e32 v77, v35
	v_add_f32_e32 v118, v35, v118
	v_max_f32_e32 v36, v150, v150
	v_max_f32_e32 v35, v118, v36
	v_sub_f32_e32 v118, v118, v35
	v_sub_f32_e32 v150, v150, v35
	v_mul_f32_e32 v118, 0x3fb8aa3b, v118
	v_mul_f32_e32 v150, 0x3fb8aa3b, v150
	v_exp_f32_e32 v118, v118
	v_exp_f32_e32 v150, v150
	v_mov_b32_e32 v78, v35
	v_add_f32_e32 v119, v35, v119
	v_max_f32_e32 v36, v151, v151
	v_max_f32_e32 v35, v119, v36
	v_sub_f32_e32 v119, v119, v35
	v_sub_f32_e32 v151, v151, v35
	v_mul_f32_e32 v119, 0x3fb8aa3b, v119
	v_mul_f32_e32 v151, 0x3fb8aa3b, v151
	v_exp_f32_e32 v119, v119
	v_exp_f32_e32 v151, v151
	v_mov_b32_e32 v79, v35
	v_add_f32_e32 v120, v35, v120
	v_max_f32_e32 v36, v152, v152
	v_max_f32_e32 v35, v120, v36
	v_sub_f32_e32 v120, v120, v35
	v_sub_f32_e32 v152, v152, v35
	v_mul_f32_e32 v120, 0x3fb8aa3b, v120
	v_mul_f32_e32 v152, 0x3fb8aa3b, v152
	v_exp_f32_e32 v120, v120
	v_exp_f32_e32 v152, v152
	v_mov_b32_e32 v80, v35
	v_add_f32_e32 v121, v35, v121
	v_max_f32_e32 v36, v153, v153
	v_max_f32_e32 v35, v121, v36
	v_sub_f32_e32 v121, v121, v35
	v_sub_f32_e32 v153, v153, v35
	v_mul_f32_e32 v121, 0x3fb8aa3b, v121
	v_mul_f32_e32 v153, 0x3fb8aa3b, v153
	v_exp_f32_e32 v121, v121
	v_exp_f32_e32 v153, v153
	v_mov_b32_e32 v24, 0
	global_store_dword v34, v24, s[2:3] offset:0
	s_waitcnt vmcnt(32)
	v_mul_f32_e32 v25, v184, v122
	v_fmac_f32_e32 v25, v24, v90
	global_store_dword v34, v25, s[2:3] offset:1024
	s_waitcnt vmcnt(32)
	v_mul_f32_e32 v24, v185, v123
	v_fmac_f32_e32 v24, v25, v91
	global_store_dword v34, v24, s[2:3] offset:2048
	s_waitcnt vmcnt(32)
	v_mul_f32_e32 v25, v186, v124
	v_fmac_f32_e32 v25, v24, v92
	global_store_dword v34, v25, s[2:3] offset:3072
	s_add_u32 s2, s2, 0x1000
	s_addc_u32 s3, s3, 0
	s_waitcnt vmcnt(32)
	v_mul_f32_e32 v24, v187, v125
	v_fmac_f32_e32 v24, v25, v93
	global_store_dword v34, v24, s[2:3] offset:0
	s_waitcnt vmcnt(32)
	v_mul_f32_e32 v25, v188, v126
	v_fmac_f32_e32 v25, v24, v94
	global_store_dword v34, v25, s[2:3] offset:1024
	s_waitcnt vmcnt(32)
	v_mul_f32_e32 v24, v189, v127
	v_fmac_f32_e32 v24, v25, v95
	global_store_dword v34, v24, s[2:3] offset:2048
	s_waitcnt vmcnt(32)
	v_mul_f32_e32 v25, v190, v128
	v_fmac_f32_e32 v25, v24, v96
	global_store_dword v34, v25, s[2:3] offset:3072
	s_add_u32 s2, s2, 0x1000
	s_addc_u32 s3, s3, 0
	s_waitcnt vmcnt(32)
	v_mul_f32_e32 v24, v191, v129
	v_fmac_f32_e32 v24, v25, v97
	global_store_dword v34, v24, s[2:3] offset:0
	s_waitcnt vmcnt(32)
	v_mul_f32_e32 v25, v192, v130
	v_fmac_f32_e32 v25, v24, v98
	global_store_dword v34, v25, s[2:3] offset:1024
	s_waitcnt vmcnt(32)
	v_mul_f32_e32 v24, v193, v131
	v_fmac_f32_e32 v24, v25, v99
	global_store_dword v34, v24, s[2:3] offset:2048
	s_waitcnt vmcnt(32)
	v_mul_f32_e32 v25, v194, v132
	v_fmac_f32_e32 v25, v24, v100
	global_store_dword v34, v25, s[2:3] offset:3072
	s_add_u32 s2, s2, 0x1000
	s_addc_u32 s3, s3, 0
	s_waitcnt vmcnt(32)
	v_mul_f32_e32 v24, v195, v133
	v_fmac_f32_e32 v24, v25, v101
	global_store_dword v34, v24, s[2:3] offset:0
	s_waitcnt vmcnt(32)
	v_mul_f32_e32 v25, v196, v134
	v_fmac_f32_e32 v25, v24, v102
	global_store_dword v34, v25, s[2:3] offset:1024
	s_waitcnt vmcnt(32)
	v_mul_f32_e32 v24, v197, v135
	v_fmac_f32_e32 v24, v25, v103
	global_store_dword v34, v24, s[2:3] offset:2048
	s_waitcnt vmcnt(32)
	v_mul_f32_e32 v25, v198, v136
	v_fmac_f32_e32 v25, v24, v104
	global_store_dword v34, v25, s[2:3] offset:3072
	s_add_u32 s2, s2, 0x1000
	s_addc_u32 s3, s3, 0
	s_waitcnt vmcnt(32)
	v_mul_f32_e32 v24, v199, v137
	v_fmac_f32_e32 v24, v25, v105
	global_store_dword v34, v24, s[2:3] offset:0
	s_waitcnt vmcnt(32)
	v_mul_f32_e32 v25, v200, v138
	v_fmac_f32_e32 v25, v24, v106
	global_store_dword v34, v25, s[2:3] offset:1024
	s_waitcnt vmcnt(32)
	v_mul_f32_e32 v24, v201, v139
	v_fmac_f32_e32 v24, v25, v107
	global_store_dword v34, v24, s[2:3] offset:2048
	s_waitcnt vmcnt(32)
	v_mul_f32_e32 v25, v202, v140
	v_fmac_f32_e32 v25, v24, v108
	global_store_dword v34, v25, s[2:3] offset:3072
	s_add_u32 s2, s2, 0x1000
	s_addc_u32 s3, s3, 0
	s_waitcnt vmcnt(32)
	v_mul_f32_e32 v24, v203, v141
	v_fmac_f32_e32 v24, v25, v109
	global_store_dword v34, v24, s[2:3] offset:0
	s_waitcnt vmcnt(32)
	v_mul_f32_e32 v25, v204, v142
	v_fmac_f32_e32 v25, v24, v110
	global_store_dword v34, v25, s[2:3] offset:1024
	s_waitcnt vmcnt(32)
	v_mul_f32_e32 v24, v205, v143
	v_fmac_f32_e32 v24, v25, v111
	global_store_dword v34, v24, s[2:3] offset:2048
	s_waitcnt vmcnt(32)
	v_mul_f32_e32 v25, v206, v144
	v_fmac_f32_e32 v25, v24, v112
	global_store_dword v34, v25, s[2:3] offset:3072
	s_add_u32 s2, s2, 0x1000
	s_addc_u32 s3, s3, 0
	s_waitcnt vmcnt(32)
	v_mul_f32_e32 v24, v207, v145
	v_fmac_f32_e32 v24, v25, v113
	global_store_dword v34, v24, s[2:3] offset:0
	s_waitcnt vmcnt(32)
	v_mul_f32_e32 v25, v208, v146
	v_fmac_f32_e32 v25, v24, v114
	global_store_dword v34, v25, s[2:3] offset:1024
	s_waitcnt vmcnt(32)
	v_mul_f32_e32 v24, v209, v147
	v_fmac_f32_e32 v24, v25, v115
	global_store_dword v34, v24, s[2:3] offset:2048
	s_waitcnt vmcnt(32)
	v_mul_f32_e32 v25, v210, v148
	v_fmac_f32_e32 v25, v24, v116
	global_store_dword v34, v25, s[2:3] offset:3072
	s_add_u32 s2, s2, 0x1000
	s_addc_u32 s3, s3, 0
	s_waitcnt vmcnt(32)
	v_mul_f32_e32 v24, v211, v149
	v_fmac_f32_e32 v24, v25, v117
	global_store_dword v34, v24, s[2:3] offset:0
	s_waitcnt vmcnt(32)
	v_mul_f32_e32 v25, v212, v150
	v_fmac_f32_e32 v25, v24, v118
	global_store_dword v34, v25, s[2:3] offset:1024
	s_waitcnt vmcnt(32)
	v_mul_f32_e32 v24, v213, v151
	v_fmac_f32_e32 v24, v25, v119
	global_store_dword v34, v24, s[2:3] offset:2048
	s_waitcnt vmcnt(32)
	v_mul_f32_e32 v25, v214, v152
	v_fmac_f32_e32 v25, v24, v120
	global_store_dword v34, v25, s[2:3] offset:3072
	s_waitcnt vmcnt(32)
	v_mul_f32_e32 v24, v215, v153
	v_fmac_f32_e32 v24, v25, v121
	s_add_u32 s6, s6, s66
	s_branch .Ld3_p2loop
.Ld3_done:
.LBB0_543:
	s_waitcnt vmcnt(0)
	s_barrier
	s_mov_b64 s[4:5], exec
	v_readlane_b32 s0, v252, 1
	v_readlane_b32 s1, v252, 2
	s_and_b64 s[0:1], s[4:5], s[0:1]
	s_mov_b64 exec, s[0:1]
	s_cbranch_execz .LBB0_595
	s_add_i32 s0, 0, 0x26f00
	v_mov_b32_e32 v0, s0
	s_waitcnt vmcnt(0) expcnt(0) lgkmcnt(0)
	ds_read_b32 v2, v0
	s_add_i32 s0, 0, 0x26f04
	v_mov_b32_e32 v0, s0
	ds_read_b32 v0, v0
	s_waitcnt lgkmcnt(1)
	v_cmp_ne_u32_e32 vcc, 0, v2
	s_cbranch_vccnz .LBB0_559
	s_add_u32 s6, s58, 0xc200
	s_addc_u32 s7, s59, 0
	s_add_u32 s8, s58, 0xc400
	s_addc_u32 s9, s59, 0
	s_add_u32 s10, s58, 0xc500
	s_addc_u32 s11, s59, 0
	s_add_u32 s12, s58, 0xc600
	s_addc_u32 s13, s59, 0
	s_add_u32 s14, s58, 0xc700
	s_addc_u32 s15, s59, 0
	s_add_u32 s16, s58, 0xc800
	s_addc_u32 s17, s59, 0
	s_add_u32 s18, s58, 0xc900
	s_addc_u32 s19, s59, 0
	s_add_u32 s20, s58, 0xca00
	s_addc_u32 s21, s59, 0
	s_add_u32 s22, s58, 0xcb00
	s_addc_u32 s23, s59, 0
	s_add_u32 s24, s58, 0xcc00
	s_addc_u32 s25, s59, 0
	s_add_u32 s26, s58, 0xcd00
	s_addc_u32 s27, s59, 0
	s_add_u32 s28, s58, 0xce00
	s_addc_u32 s29, s59, 0
	s_add_u32 s30, s58, 0xcf00
	s_addc_u32 s31, s59, 0
	s_add_u32 s34, s58, 0xd000
	s_addc_u32 s35, s59, 0
	s_add_u32 s36, s58, 0xd100
	s_addc_u32 s37, s59, 0
	s_add_u32 s38, s58, 0xd200
	s_addc_u32 s39, s59, 0
	s_add_u32 s40, s58, 0xd300
	s_addc_u32 s41, s59, 0
	s_mov_b32 s0, 1
	v_mov_b32_e32 v16, 0
	s_branch .LBB0_547
